# phase 14 now empty: phase loop steps 13->15 directly, one grid barrier fewer
# speedup vs baseline: 1.0254x; 1.0039x over previous
.LBB0_1159:
	v_readlane_b32 s26, v255, 5
	s_add_i32 s24, s66, 1
	s_cmp_eq_u32 s66, 13
	s_cselect_b32 s24, 15, s24
	v_readlane_b32 s27, v255, 6
	s_cmp_ge_i32 s24, s27
	s_mov_b64 s[4:5], -1
	s_cbranch_scc0 .LBB0_1160
	s_getpc_b64 s[98:99]
